# mlstm_local gate chain: four gate loads per token pair issued together (one wait instead of two)
# baseline (speedup 1.0000x reference)
; __device__ __forceinline__ float logsig(float x) { return fminf(x, 0.f) - log1pf(__expf(-fabsf(x))); }
; __device__ __forceinline__ void gate_chain(const float* gif, int b, int h, int j, float* sm) {
;     ...
;     for (int i = wave; i <= j; i += 8) {
;         const int Li = i == 0 ? 16 : 128; const int rowb = i == 0 ? ROW_META : b * 2048 + (i - 1) * 128;
;         const int t0 = 2 * lane;
;         float f0 = 0.f, f1 = 0.f, i0 = -INFINITY, i1 = -INFINITY;
;         if (t0 < Li) { const float* gp = gif + (size_t)(rowb + t0) * 8; i0 = gp[h]; f0 = logsig(gp[4 + h]); i1 = gp[8 + h]; f1 = logsig(gp[12 + h]); }
.LBB0_294:
	s_cmpk_gt_i32 s70, 0xff
	s_mov_b64 s[0:1], -1
	s_cbranch_scc0 .LBB0_312
	s_and_b32 s34, s70, 3
	s_and_saveexec_b64 s[10:11], s[56:57]
	s_cbranch_execz .LBB0_301
	v_mov_b32_e32 v0, 0xff800000
	v_mov_b32_e32 v2, 0
	v_mov_b32_e32 v1, v0
	v_mov_b32_e32 v3, 0
	s_and_saveexec_b64 s[16:17], s[62:63]
	s_cbranch_execz .LBB0_298
	s_lshl_b32 s84, s34, 2
	v_lshl_add_u64 v[0:1], v[68:69], 0, s[84:85]
	v_add_co_u32_e32 v4, vcc, 0x4541000, v0
	s_nop 1
	v_addc_co_u32_e32 v5, vcc, 0, v1, vcc
	global_load_dword v0, v[4:5], off
	global_load_dword v1, v[4:5], off offset:16
	global_load_dword v120, v[4:5], off offset:32
	global_load_dword v121, v[4:5], off offset:48
	s_waitcnt vmcnt(0)
	v_max_f32_e32 v2, v1, v1
	v_mul_f32_e64 v1, |v1|, s51
	v_exp_f32_e32 v28, v1
	v_min_f32_e32 v3, 0, v2
	v_add_f32_e32 v1, 1.0, v28
	v_add_f32_e32 v2, -1.0, v1
	v_sub_f32_e32 v6, v2, v1
	v_add_f32_e32 v6, 1.0, v6
	v_sub_f32_e32 v2, v28, v2
	v_add_f32_e32 v2, v2, v6
	v_frexp_mant_f32_e32 v6, v1
	v_cmp_gt_f32_e32 vcc, s6, v6
	v_cvt_f64_f32_e32 v[6:7], v1
	v_frexp_exp_i32_f64_e32 v6, v[6:7]
	v_subbrev_co_u32_e32 v6, vcc, 0, v6, vcc
	v_sub_u32_e32 v7, 0, v6
	v_ldexp_f32 v9, v1, v7
	v_mov_b32_e32 v1, v120
	s_nop 0
	v_mov_b32_e32 v4, v121
	v_ldexp_f32 v11, v2, v7
	v_cmp_lt_f32_e64 s[0:1], |v28|, s30
	s_nop 0
	v_max_f32_e32 v2, v4, v4
	v_mul_f32_e64 v4, |v4|, s51
	v_exp_f32_e32 v29, v4
	v_min_f32_e32 v2, 0, v2
	v_add_f32_e32 v7, 1.0, v29
	v_add_f32_e32 v4, -1.0, v7
	v_sub_f32_e32 v5, v4, v7
	v_add_f32_e32 v5, 1.0, v5
	v_sub_f32_e32 v4, v29, v4
	v_add_f32_e32 v10, v4, v5
	v_frexp_mant_f32_e32 v4, v7
	v_cmp_gt_f32_e32 vcc, s6, v4
	v_cvt_f64_f32_e32 v[4:5], v7
	v_frexp_exp_i32_f64_e32 v4, v[4:5]
	v_subbrev_co_u32_e32 v26, vcc, 0, v4, vcc
	v_sub_u32_e32 v4, 0, v26
	v_ldexp_f32 v8, v7, v4
	v_ldexp_f32 v10, v10, v4
	v_pk_add_f32 v[4:5], v[8:9], 1.0 op_sel_hi:[1,0]
	v_pk_add_f32 v[18:19], v[8:9], -1.0 op_sel_hi:[1,0]
	v_pk_add_f32 v[12:13], v[4:5], -1.0 op_sel_hi:[1,0]
	v_pk_add_f32 v[20:21], v[18:19], 1.0 op_sel_hi:[1,0]
	v_pk_add_f32 v[12:13], v[8:9], v[12:13] neg_lo:[0,1] neg_hi:[0,1]
	v_pk_add_f32 v[8:9], v[8:9], v[20:21] neg_lo:[0,1] neg_hi:[0,1]
	v_pk_add_f32 v[12:13], v[10:11], v[12:13]
	v_pk_add_f32 v[8:9], v[10:11], v[8:9]
	v_pk_add_f32 v[14:15], v[4:5], v[12:13]
	v_pk_add_f32 v[10:11], v[18:19], v[8:9]
	v_rcp_f32_e32 v17, v15
	v_rcp_f32_e32 v16, v14
	v_pk_add_f32 v[4:5], v[14:15], v[4:5] neg_lo:[0,1] neg_hi:[0,1]
	v_pk_add_f32 v[18:19], v[10:11], v[18:19] neg_lo:[0,1] neg_hi:[0,1]
	v_pk_add_f32 v[4:5], v[12:13], v[4:5] neg_lo:[0,1] neg_hi:[0,1]
	v_pk_mul_f32 v[12:13], v[10:11], v[16:17]
	v_pk_add_f32 v[8:9], v[8:9], v[18:19] neg_lo:[0,1] neg_hi:[0,1]
	v_pk_mul_f32 v[18:19], v[14:15], v[12:13]
	v_cmp_neq_f32_e32 vcc, s7, v29
	v_pk_fma_f32 v[20:21], v[12:13], v[14:15], v[18:19] neg_lo:[0,0,1] neg_hi:[0,0,1]
	s_nop 0
	v_pk_fma_f32 v[20:21], v[12:13], v[4:5], v[20:21]
	s_nop 0
	v_pk_add_f32 v[22:23], v[18:19], v[20:21]
	s_nop 0
	v_pk_add_f32 v[24:25], v[10:11], v[22:23] neg_lo:[0,1] neg_hi:[0,1]
	v_pk_add_f32 v[18:19], v[22:23], v[18:19] neg_lo:[0,1] neg_hi:[0,1]
	v_pk_add_f32 v[10:11], v[10:11], v[24:25] neg_lo:[0,1] neg_hi:[0,1]
	s_nop 0
	v_pk_add_f32 v[10:11], v[10:11], v[22:23] neg_lo:[0,1] neg_hi:[0,1]
	s_nop 0
	v_pk_add_f32 v[8:9], v[8:9], v[10:11]
	v_pk_add_f32 v[10:11], v[18:19], v[20:21] neg_lo:[0,1] neg_hi:[0,1]
	s_nop 0
	v_pk_add_f32 v[8:9], v[10:11], v[8:9]
	s_nop 0
	v_pk_add_f32 v[10:11], v[24:25], v[8:9]
	s_nop 0
	v_pk_mul_f32 v[18:19], v[16:17], v[10:11]
	s_nop 0
	v_pk_mul_f32 v[20:21], v[14:15], v[18:19]
	s_nop 0
	v_pk_fma_f32 v[14:15], v[18:19], v[14:15], v[20:21] neg_lo:[0,0,1] neg_hi:[0,0,1]
	s_nop 0
	v_pk_fma_f32 v[4:5], v[18:19], v[4:5], v[14:15]
	v_pk_add_f32 v[14:15], v[24:25], v[10:11] neg_lo:[0,1] neg_hi:[0,1]
	s_nop 0
	v_pk_add_f32 v[8:9], v[8:9], v[14:15]
	v_pk_add_f32 v[14:15], v[20:21], v[4:5]
	s_nop 0
	v_pk_add_f32 v[22:23], v[10:11], v[14:15] neg_lo:[0,1] neg_hi:[0,1]
	v_pk_add_f32 v[20:21], v[14:15], v[20:21] neg_lo:[0,1] neg_hi:[0,1]
	v_pk_add_f32 v[10:11], v[10:11], v[22:23] neg_lo:[0,1] neg_hi:[0,1]
	v_pk_add_f32 v[4:5], v[20:21], v[4:5] neg_lo:[0,1] neg_hi:[0,1]
	v_pk_add_f32 v[10:11], v[10:11], v[14:15] neg_lo:[0,1] neg_hi:[0,1]
	s_nop 0
	v_pk_add_f32 v[8:9], v[8:9], v[10:11]
	s_nop 0
	v_pk_add_f32 v[4:5], v[4:5], v[8:9]
; __device__ __forceinline__ float logsig(float x) { return fminf(x, 0.f) - log1pf(__expf(-fabsf(x))); }
; __device__ __forceinline__ void gate_chain(const float* gif, int b, int h, int j, float* sm) {
;     ...
;         if (t0 < Li) { const float* gp = gif + (size_t)(rowb + t0) * 8; i0 = gp[h]; f0 = logsig(gp[4 + h]); i1 = gp[8 + h]; f1 = logsig(gp[12 + h]); }
	v_pk_add_f32 v[8:9], v[12:13], v[18:19]
	v_pk_add_f32 v[4:5], v[22:23], v[4:5]
	v_pk_add_f32 v[10:11], v[8:9], v[12:13] neg_lo:[0,1] neg_hi:[0,1]
	v_pk_mul_f32 v[4:5], v[16:17], v[4:5]
	v_pk_add_f32 v[10:11], v[18:19], v[10:11] neg_lo:[0,1] neg_hi:[0,1]
	s_nop 0
	v_pk_add_f32 v[4:5], v[10:11], v[4:5]
	s_nop 0
	v_pk_add_f32 v[12:13], v[8:9], v[4:5]
	s_nop 0
	v_pk_add_f32 v[8:9], v[12:13], v[8:9] neg_lo:[0,1] neg_hi:[0,1]
	v_pk_mul_f32 v[16:17], v[12:13], v[12:13]
	v_pk_add_f32 v[8:9], v[4:5], v[8:9] neg_lo:[0,1] neg_hi:[0,1]
	v_pk_fma_f32 v[4:5], v[16:17], s[88:89], v[76:77] op_sel_hi:[1,0,0]
	v_ldexp_f32 v15, v13, 1
	v_ldexp_f32 v11, v9, 1
	v_pk_fma_f32 v[4:5], v[16:17], v[4:5], s[90:91] op_sel_hi:[1,1,0]
	v_ldexp_f32 v14, v12, 1
	v_ldexp_f32 v18, v8, 1
	v_pk_mul_f32 v[8:9], v[12:13], v[16:17]
	v_cvt_f32_i32_e32 v13, v6
	v_cvt_f32_i32_e32 v12, v26
	v_pk_mul_f32 v[16:17], v[8:9], v[4:5]
	v_mov_b32_e32 v19, v11
	v_pk_add_f32 v[4:5], v[14:15], v[16:17]
	v_pk_mul_f32 v[6:7], v[12:13], s[92:93] op_sel_hi:[1,0]
	v_pk_add_f32 v[14:15], v[4:5], v[14:15] neg_lo:[0,1] neg_hi:[0,1]
	v_pk_fma_f32 v[8:9], v[12:13], s[92:93], v[6:7] op_sel_hi:[1,0,1] neg_lo:[0,0,1] neg_hi:[0,0,1]
	v_pk_add_f32 v[20:21], v[16:17], v[14:15] neg_lo:[0,1] neg_hi:[0,1]
	v_pk_fma_f32 v[8:9], v[12:13], s[8:9], v[8:9] op_sel_hi:[1,0,1]
	v_pk_add_f32 v[16:17], v[18:19], v[20:21]
	v_mov_b32_e32 v15, v21
	v_mov_b32_e32 v19, v17
	v_mov_b32_e32 v21, v5
	v_pk_add_f32 v[12:13], v[6:7], v[8:9]
	v_mov_b32_e32 v14, v6
	v_mov_b32_e32 v10, v8
	v_pk_add_f32 v[20:21], v[18:19], v[20:21]
	v_pk_add_f32 v[18:19], v[4:5], v[16:17]
	v_pk_add_f32 v[14:15], v[14:15], v[10:11]
	v_pk_add_f32 v[10:11], v[12:13], v[18:19]
	v_mov_b32_e32 v22, v18
	v_mov_b32_e32 v23, v11
	v_mov_b32_e32 v24, v4
	v_mov_b32_e32 v25, v13
	v_pk_add_f32 v[22:23], v[22:23], v[24:25] neg_lo:[0,1] neg_hi:[0,1]
	v_mov_b32_e32 v24, v12
	v_mov_b32_e32 v25, v11
	v_mov_b32_e32 v26, v6
	v_mov_b32_e32 v27, v23
	v_pk_add_f32 v[24:25], v[24:25], v[26:27] neg_lo:[0,1] neg_hi:[0,1]
	v_mov_b32_e32 v27, v13
	v_mov_b32_e32 v30, v10
	v_mov_b32_e32 v31, v13
	v_mov_b32_e32 v13, v7
	v_mov_b32_e32 v26, v8
	v_pk_add_f32 v[6:7], v[30:31], v[12:13] neg_lo:[0,1] neg_hi:[0,1]
	v_pk_add_f32 v[26:27], v[26:27], v[24:25] neg_lo:[0,1] neg_hi:[0,1]
	v_mov_b32_e32 v25, v7
	v_pk_add_f32 v[12:13], v[8:9], v[24:25] neg_lo:[0,1] neg_hi:[0,1]
	v_pk_add_f32 v[24:25], v[18:19], v[4:5] neg_lo:[0,1] neg_hi:[0,1]
	v_pk_add_f32 v[20:21], v[20:21], v[22:23] neg_lo:[0,1] neg_hi:[0,1]
	v_mov_b32_e32 v22, v10
	v_mov_b32_e32 v23, v19
	v_mov_b32_e32 v4, v6
	v_pk_add_f32 v[4:5], v[22:23], v[4:5] neg_lo:[0,1] neg_hi:[0,1]
	v_mov_b32_e32 v19, v9
	v_pk_add_f32 v[4:5], v[14:15], v[4:5] neg_lo:[0,1] neg_hi:[0,1]
	v_pk_add_f32 v[6:7], v[18:19], v[6:7] neg_lo:[0,1] neg_hi:[0,1]
	v_pk_add_f32 v[14:15], v[20:21], v[26:27]
	v_mov_b32_e32 v27, v7
	v_mov_b32_e32 v21, v5
	v_pk_add_f32 v[8:9], v[6:7], v[4:5]
	v_pk_add_f32 v[4:5], v[26:27], v[20:21]
	v_mov_b32_e32 v6, v14
	v_pk_add_f32 v[4:5], v[4:5], v[12:13] neg_lo:[0,1] neg_hi:[0,1]
	v_mov_b32_e32 v7, v9
	v_pk_add_f32 v[16:17], v[16:17], v[24:25] neg_lo:[0,1] neg_hi:[0,1]
	v_pk_add_f32 v[6:7], v[6:7], v[4:5] neg_lo:[0,1] neg_hi:[0,1]
	v_pk_add_f32 v[4:5], v[16:17], v[4:5] neg_lo:[0,1] neg_hi:[0,1]
	v_pk_add_f32 v[6:7], v[26:27], v[6:7] neg_lo:[0,1] neg_hi:[0,1]
	s_nop 0
	v_pk_add_f32 v[4:5], v[4:5], v[6:7]
	v_pk_add_f32 v[6:7], v[8:9], v[14:15]
	s_nop 0
	v_pk_add_f32 v[8:9], v[10:11], v[6:7]
	s_nop 0
	v_pk_add_f32 v[10:11], v[8:9], v[10:11] neg_lo:[0,1] neg_hi:[0,1]
	s_nop 0
	v_pk_add_f32 v[6:7], v[6:7], v[10:11] neg_lo:[0,1] neg_hi:[0,1]
	s_nop 0
	v_pk_add_f32 v[4:5], v[4:5], v[6:7]
	s_nop 0
	v_pk_add_f32 v[4:5], v[8:9], v[4:5]
	s_nop 0
	v_cndmask_b32_e32 v4, v99, v4, vcc
	v_cmp_neq_f32_e32 vcc, s7, v28
	s_nop 1
	v_cndmask_b32_e32 v5, v99, v5, vcc
	v_cmp_ngt_f32_e32 vcc, -1.0, v28
	s_nop 1
	v_cndmask_b32_e32 v5, v100, v5, vcc
	v_cmp_ngt_f32_e32 vcc, -1.0, v29
	s_nop 1
	v_cndmask_b32_e32 v4, v100, v4, vcc
	v_cmp_neq_f32_e32 vcc, -1.0, v29
	s_nop 1
	v_cndmask_b32_e32 v4, v101, v4, vcc
	v_cmp_neq_f32_e32 vcc, -1.0, v28
	s_nop 1
	v_cndmask_b32_e32 v5, v101, v5, vcc
	v_cmp_lt_f32_e64 vcc, |v29|, s30
	v_cndmask_b32_e64 v5, v5, v28, s[0:1]
	s_nop 0
	v_cndmask_b32_e32 v4, v4, v29, vcc
	v_pk_add_f32 v[2:3], v[2:3], v[4:5] neg_lo:[0,1] neg_hi:[0,1]

; __device__ __forceinline__ float logsig(float x) { return fminf(x, 0.f) - log1pf(__expf(-fabsf(x))); }
; __device__ __forceinline__ void gate_chain(const float* gif, int b, int h, int j, float* sm) {
;     ...
;     for (int i = wave; i <= j; i += 8) {
;         const int Li = i == 0 ? 16 : 128; const int rowb = i == 0 ? ROW_META : b * 2048 + (i - 1) * 128;
;         const int t0 = 2 * lane;
;         float f0 = 0.f, f1 = 0.f, i0 = -INFINITY, i1 = -INFINITY;
;         if (t0 < Li) { const float* gp = gif + (size_t)(rowb + t0) * 8; i0 = gp[h]; f0 = logsig(gp[4 + h]); i1 = gp[8 + h]; f1 = logsig(gp[12 + h]); }
.LBB0_316:
	v_cmp_eq_u32_e32 vcc, 0, v38
	s_waitcnt lgkmcnt(0)
	v_mov_b32_e32 v4, 0
	v_mov_b32_e32 v1, 0xff800000
	v_cndmask_b32_e64 v0, v105, 16, vcc
	v_cmp_lt_u32_e64 s[0:1], v81, v0
	v_mov_b32_e32 v0, 0xff800000
	v_mov_b32_e32 v5, 0
	s_and_saveexec_b64 s[54:55], s[0:1]
	s_cbranch_execz .LBB0_318
	v_cndmask_b32_e32 v0, v36, v106, vcc
	v_or_b32_e32 v0, v0, v81
	v_ashrrev_i32_e32 v1, 31, v0
	v_lshlrev_b64 v[0:1], 5, v[0:1]
	v_lshl_add_u64 v[4:5], s[34:35], 0, v[0:1]
	global_load_dword v0, v[4:5], off
	global_load_dword v1, v[4:5], off offset:16
	global_load_dword v120, v[4:5], off offset:32
	global_load_dword v121, v[4:5], off offset:48
	s_waitcnt vmcnt(0)
	v_max_f32_e32 v2, v1, v1
	v_mul_f32_e64 v1, |v1|, s51
	v_exp_f32_e32 v39, v1
	v_min_f32_e32 v3, 0, v2
	v_add_f32_e32 v1, 1.0, v39
	v_add_f32_e32 v2, -1.0, v1
	v_sub_f32_e32 v6, v2, v1
	v_add_f32_e32 v6, 1.0, v6
	v_sub_f32_e32 v2, v39, v2
	v_add_f32_e32 v2, v2, v6
	v_frexp_mant_f32_e32 v6, v1
	v_cmp_gt_f32_e32 vcc, s6, v6
	v_cvt_f64_f32_e32 v[6:7], v1
	v_frexp_exp_i32_f64_e32 v6, v[6:7]
	v_subbrev_co_u32_e32 v8, vcc, 0, v6, vcc
	v_sub_u32_e32 v6, 0, v8
	v_ldexp_f32 v7, v1, v6
	v_mov_b32_e32 v1, v120
	s_nop 0
	v_mov_b32_e32 v4, v121
	v_ldexp_f32 v11, v2, v6
	v_cmp_lt_f32_e64 s[0:1], |v39|, s30
	s_nop 0
	v_max_f32_e32 v2, v4, v4
	v_mul_f32_e64 v4, |v4|, s51
	v_exp_f32_e32 v40, v4
	v_min_f32_e32 v2, 0, v2
	v_add_f32_e32 v6, 1.0, v40
	v_add_f32_e32 v4, -1.0, v6
	v_sub_f32_e32 v5, v4, v6
	v_add_f32_e32 v5, 1.0, v5
	v_sub_f32_e32 v4, v40, v4
	v_add_f32_e32 v9, v4, v5
	v_frexp_mant_f32_e32 v4, v6
	v_cmp_gt_f32_e32 vcc, s6, v4
	v_cvt_f64_f32_e32 v[4:5], v6
	v_frexp_exp_i32_f64_e32 v4, v[4:5]
	v_subbrev_co_u32_e32 v26, vcc, 0, v4, vcc
	v_sub_u32_e32 v4, 0, v26
	v_ldexp_f32 v6, v6, v4
	v_ldexp_f32 v10, v9, v4
	v_pk_add_f32 v[4:5], v[6:7], 1.0 op_sel_hi:[1,0]
	v_pk_add_f32 v[18:19], v[6:7], -1.0 op_sel_hi:[1,0]
	v_pk_add_f32 v[12:13], v[4:5], -1.0 op_sel_hi:[1,0]
	v_pk_add_f32 v[20:21], v[18:19], 1.0 op_sel_hi:[1,0]
	v_pk_add_f32 v[12:13], v[6:7], v[12:13] neg_lo:[0,1] neg_hi:[0,1]
	v_pk_add_f32 v[6:7], v[6:7], v[20:21] neg_lo:[0,1] neg_hi:[0,1]
	v_pk_add_f32 v[12:13], v[10:11], v[12:13]
	v_pk_add_f32 v[6:7], v[10:11], v[6:7]
	v_pk_add_f32 v[14:15], v[4:5], v[12:13]
	v_pk_add_f32 v[10:11], v[18:19], v[6:7]
	v_rcp_f32_e32 v17, v15
	v_rcp_f32_e32 v16, v14
	v_pk_add_f32 v[4:5], v[14:15], v[4:5] neg_lo:[0,1] neg_hi:[0,1]
	v_pk_add_f32 v[18:19], v[10:11], v[18:19] neg_lo:[0,1] neg_hi:[0,1]
	v_pk_add_f32 v[4:5], v[12:13], v[4:5] neg_lo:[0,1] neg_hi:[0,1]
	v_pk_mul_f32 v[12:13], v[10:11], v[16:17]
	v_pk_add_f32 v[6:7], v[6:7], v[18:19] neg_lo:[0,1] neg_hi:[0,1]
	v_pk_mul_f32 v[18:19], v[14:15], v[12:13]
	v_cmp_neq_f32_e32 vcc, s7, v40
	v_pk_fma_f32 v[20:21], v[12:13], v[14:15], v[18:19] neg_lo:[0,0,1] neg_hi:[0,0,1]
	s_nop 0
	v_pk_fma_f32 v[20:21], v[12:13], v[4:5], v[20:21]
	s_nop 0
	v_pk_add_f32 v[22:23], v[18:19], v[20:21]
	s_nop 0
	v_pk_add_f32 v[24:25], v[10:11], v[22:23] neg_lo:[0,1] neg_hi:[0,1]
	v_pk_add_f32 v[18:19], v[22:23], v[18:19] neg_lo:[0,1] neg_hi:[0,1]
	v_pk_add_f32 v[10:11], v[10:11], v[24:25] neg_lo:[0,1] neg_hi:[0,1]
	s_nop 0
	v_pk_add_f32 v[10:11], v[10:11], v[22:23] neg_lo:[0,1] neg_hi:[0,1]
	s_nop 0
	v_pk_add_f32 v[6:7], v[6:7], v[10:11]
	v_pk_add_f32 v[10:11], v[18:19], v[20:21] neg_lo:[0,1] neg_hi:[0,1]
	s_nop 0
	v_pk_add_f32 v[6:7], v[10:11], v[6:7]
	s_nop 0
	v_pk_add_f32 v[10:11], v[24:25], v[6:7]
	s_nop 0
	v_pk_mul_f32 v[18:19], v[16:17], v[10:11]
	s_nop 0
	v_pk_mul_f32 v[20:21], v[14:15], v[18:19]
	s_nop 0
	v_pk_fma_f32 v[14:15], v[18:19], v[14:15], v[20:21] neg_lo:[0,0,1] neg_hi:[0,0,1]
	s_nop 0
	v_pk_fma_f32 v[4:5], v[18:19], v[4:5], v[14:15]
	v_pk_add_f32 v[14:15], v[24:25], v[10:11] neg_lo:[0,1] neg_hi:[0,1]
	s_nop 0
	v_pk_add_f32 v[6:7], v[6:7], v[14:15]
	v_pk_add_f32 v[14:15], v[20:21], v[4:5]
	s_nop 0
	v_pk_add_f32 v[22:23], v[10:11], v[14:15] neg_lo:[0,1] neg_hi:[0,1]
	v_pk_add_f32 v[20:21], v[14:15], v[20:21] neg_lo:[0,1] neg_hi:[0,1]
	v_pk_add_f32 v[10:11], v[10:11], v[22:23] neg_lo:[0,1] neg_hi:[0,1]
	v_pk_add_f32 v[4:5], v[20:21], v[4:5] neg_lo:[0,1] neg_hi:[0,1]
	v_pk_add_f32 v[10:11], v[10:11], v[14:15] neg_lo:[0,1] neg_hi:[0,1]
	s_nop 0
	v_pk_add_f32 v[6:7], v[6:7], v[10:11]
	s_nop 0
	v_pk_add_f32 v[4:5], v[4:5], v[6:7]
	v_pk_add_f32 v[6:7], v[12:13], v[18:19]
; __device__ __forceinline__ float logsig(float x) { return fminf(x, 0.f) - log1pf(__expf(-fabsf(x))); }
; __device__ __forceinline__ void gate_chain(const float* gif, int b, int h, int j, float* sm) {
;     ...
;         if (t0 < Li) { const float* gp = gif + (size_t)(rowb + t0) * 8; i0 = gp[h]; f0 = logsig(gp[4 + h]); i1 = gp[8 + h]; f1 = logsig(gp[12 + h]); }
	v_pk_add_f32 v[4:5], v[22:23], v[4:5]
	v_pk_add_f32 v[10:11], v[6:7], v[12:13] neg_lo:[0,1] neg_hi:[0,1]
	v_pk_mul_f32 v[4:5], v[16:17], v[4:5]
	v_pk_add_f32 v[10:11], v[18:19], v[10:11] neg_lo:[0,1] neg_hi:[0,1]
	s_nop 0
	v_pk_add_f32 v[4:5], v[10:11], v[4:5]
	s_nop 0
	v_pk_add_f32 v[10:11], v[6:7], v[4:5]
	s_nop 0
	v_pk_add_f32 v[6:7], v[10:11], v[6:7] neg_lo:[0,1] neg_hi:[0,1]
	v_pk_mul_f32 v[14:15], v[10:11], v[10:11]
	v_pk_add_f32 v[6:7], v[4:5], v[6:7] neg_lo:[0,1] neg_hi:[0,1]
	v_pk_fma_f32 v[4:5], v[14:15], s[88:89], v[76:77] op_sel_hi:[1,0,0]
	v_ldexp_f32 v9, v7, 1
	v_pk_fma_f32 v[4:5], v[14:15], v[4:5], s[90:91] op_sel_hi:[1,1,0]
	v_ldexp_f32 v18, v6, 1
	v_pk_mul_f32 v[6:7], v[10:11], v[14:15]
	v_cvt_f32_i32_e32 v15, v8
	v_cvt_f32_i32_e32 v14, v26
	v_ldexp_f32 v13, v11, 1
	v_ldexp_f32 v12, v10, 1
	v_pk_mul_f32 v[16:17], v[6:7], v[4:5]
	v_pk_mul_f32 v[10:11], v[14:15], s[92:93] op_sel_hi:[1,0]
	v_pk_add_f32 v[4:5], v[12:13], v[16:17]
	v_mov_b32_e32 v19, v9
	v_pk_add_f32 v[12:13], v[4:5], v[12:13] neg_lo:[0,1] neg_hi:[0,1]
	v_pk_fma_f32 v[6:7], v[14:15], s[92:93], v[10:11] op_sel_hi:[1,0,1] neg_lo:[0,0,1] neg_hi:[0,0,1]
	v_pk_add_f32 v[20:21], v[16:17], v[12:13] neg_lo:[0,1] neg_hi:[0,1]
	v_pk_fma_f32 v[6:7], v[14:15], s[8:9], v[6:7] op_sel_hi:[1,0,1]
	v_pk_add_f32 v[16:17], v[18:19], v[20:21]
	v_mov_b32_e32 v13, v21
	v_mov_b32_e32 v19, v17
	v_mov_b32_e32 v21, v5
	v_pk_add_f32 v[14:15], v[10:11], v[6:7]
	v_mov_b32_e32 v12, v10
	v_mov_b32_e32 v8, v6
	v_pk_add_f32 v[20:21], v[18:19], v[20:21]
	v_pk_add_f32 v[18:19], v[4:5], v[16:17]
	v_pk_add_f32 v[12:13], v[12:13], v[8:9]
	v_pk_add_f32 v[8:9], v[14:15], v[18:19]
	v_mov_b32_e32 v22, v18
	v_mov_b32_e32 v23, v9
	v_mov_b32_e32 v24, v4
	v_mov_b32_e32 v25, v15
	v_pk_add_f32 v[22:23], v[22:23], v[24:25] neg_lo:[0,1] neg_hi:[0,1]
	v_mov_b32_e32 v24, v14
	v_mov_b32_e32 v25, v9
	v_mov_b32_e32 v26, v10
	v_mov_b32_e32 v27, v23
	v_pk_add_f32 v[24:25], v[24:25], v[26:27] neg_lo:[0,1] neg_hi:[0,1]
	v_mov_b32_e32 v27, v15
	v_mov_b32_e32 v28, v8
	v_mov_b32_e32 v29, v15
	v_mov_b32_e32 v15, v11
	v_mov_b32_e32 v26, v6
	v_pk_add_f32 v[10:11], v[28:29], v[14:15] neg_lo:[0,1] neg_hi:[0,1]
	v_pk_add_f32 v[26:27], v[26:27], v[24:25] neg_lo:[0,1] neg_hi:[0,1]
	v_mov_b32_e32 v25, v11
	v_pk_add_f32 v[14:15], v[6:7], v[24:25] neg_lo:[0,1] neg_hi:[0,1]
	v_pk_add_f32 v[24:25], v[18:19], v[4:5] neg_lo:[0,1] neg_hi:[0,1]
	v_pk_add_f32 v[20:21], v[20:21], v[22:23] neg_lo:[0,1] neg_hi:[0,1]
	v_mov_b32_e32 v22, v8
	v_mov_b32_e32 v23, v19
	v_mov_b32_e32 v4, v10
	v_pk_add_f32 v[4:5], v[22:23], v[4:5] neg_lo:[0,1] neg_hi:[0,1]
	v_mov_b32_e32 v19, v7
	v_pk_add_f32 v[4:5], v[12:13], v[4:5] neg_lo:[0,1] neg_hi:[0,1]
	v_pk_add_f32 v[6:7], v[18:19], v[10:11] neg_lo:[0,1] neg_hi:[0,1]
	v_pk_add_f32 v[12:13], v[20:21], v[26:27]
	v_mov_b32_e32 v27, v7
	v_mov_b32_e32 v21, v5
	v_pk_add_f32 v[10:11], v[6:7], v[4:5]
	v_pk_add_f32 v[4:5], v[26:27], v[20:21]
	v_mov_b32_e32 v6, v12
	v_pk_add_f32 v[4:5], v[4:5], v[14:15] neg_lo:[0,1] neg_hi:[0,1]
	v_mov_b32_e32 v7, v11
	v_pk_add_f32 v[16:17], v[16:17], v[24:25] neg_lo:[0,1] neg_hi:[0,1]
	v_pk_add_f32 v[6:7], v[6:7], v[4:5] neg_lo:[0,1] neg_hi:[0,1]
	v_pk_add_f32 v[4:5], v[16:17], v[4:5] neg_lo:[0,1] neg_hi:[0,1]
	v_pk_add_f32 v[6:7], v[26:27], v[6:7] neg_lo:[0,1] neg_hi:[0,1]
	s_nop 0
	v_pk_add_f32 v[4:5], v[4:5], v[6:7]
	v_pk_add_f32 v[6:7], v[10:11], v[12:13]
	s_nop 0
	v_pk_add_f32 v[10:11], v[8:9], v[6:7]
	s_nop 0
	v_pk_add_f32 v[8:9], v[10:11], v[8:9] neg_lo:[0,1] neg_hi:[0,1]
	s_nop 0
	v_pk_add_f32 v[6:7], v[6:7], v[8:9] neg_lo:[0,1] neg_hi:[0,1]
	s_nop 0
	v_pk_add_f32 v[4:5], v[4:5], v[6:7]
	s_nop 0
	v_pk_add_f32 v[4:5], v[10:11], v[4:5]
	s_nop 0
	v_cndmask_b32_e32 v4, v99, v4, vcc
	v_cmp_neq_f32_e32 vcc, s7, v39
	s_nop 1
	v_cndmask_b32_e32 v5, v99, v5, vcc
	v_cmp_ngt_f32_e32 vcc, -1.0, v39
	s_nop 1
	v_cndmask_b32_e32 v5, v100, v5, vcc
	v_cmp_ngt_f32_e32 vcc, -1.0, v40
	s_nop 1
	v_cndmask_b32_e32 v4, v100, v4, vcc
	v_cmp_neq_f32_e32 vcc, -1.0, v40
	s_nop 1
	v_cndmask_b32_e32 v4, v101, v4, vcc
	v_cmp_neq_f32_e32 vcc, -1.0, v39
	s_nop 1
	v_cndmask_b32_e32 v5, v101, v5, vcc
	v_cmp_lt_f32_e64 vcc, |v40|, s30
	v_cndmask_b32_e64 v5, v5, v39, s[0:1]
	s_nop 0
	v_cndmask_b32_e32 v4, v4, v40, vcc
	v_pk_add_f32 v[4:5], v[2:3], v[4:5] neg_lo:[0,1] neg_hi:[0,1]
